# GEMM main loops: redundant mid-phase s_setprio 0/1 pair removed (priority stays raised across the 32-MFMA phase)
# baseline (speedup 1.0000x reference)
.LBB0_163:
	s_add_u32 s6, s0, 0xfffc0080
	s_addc_u32 s7, s1, -1
	s_add_i32 s50, 0, 0x10000
	s_cmp_eq_u32 s49, 12
	s_cselect_b32 s29, s23, s7
	s_cselect_b32 s28, s31, s6
	s_cselect_b32 s7, s21, s48
	s_cselect_b32 s6, s34, s35
	s_add_i32 s52, 0, 0x14000
	v_add_u32_e32 v104, s50, v220
	v_add_u32_e32 v174, s52, v220
	ds_read_b128 v[88:91], v104
	ds_read_b128 v[92:95], v104 offset:1024
	ds_read_b128 v[96:99], v104 offset:2048
	ds_read_b128 v[104:107], v104 offset:3072
	ds_read_b128 v[160:163], v174
	ds_read_b128 v[164:167], v174 offset:1024
	ds_read_b128 v[168:171], v174 offset:2048
	ds_read_b128 v[184:187], v174 offset:3072
	v_lshl_add_u64 v[216:217], s[0:1], 0, v[156:157]
	s_add_i32 m0, s41, 0xc000
	ds_read_b128 v[188:191], v227
	ds_read_b128 v[192:195], v227 offset:1024
	ds_read_b128 v[196:199], v227 offset:2048
	ds_read_b128 v[200:203], v227 offset:3072
	ds_read_b128 v[204:207], v227 offset:4096
	ds_read_b128 v[208:211], v227 offset:5120
	ds_read_b128 v[212:215], v227 offset:6144
	ds_read_b128 v[228:231], v227 offset:7168
	global_load_lds_dwordx4 v[216:217], off
	v_lshl_add_u64 v[216:217], s[0:1], 0, v[158:159]
	s_add_i32 m0, s41, 0xe000
	s_nop 0
	global_load_lds_dwordx4 v[216:217], off
	s_waitcnt vmcnt(8)
	s_waitcnt lgkmcnt(0)
	s_barrier
	s_setprio 1
	s_waitcnt lgkmcnt(0)
	v_mfma_f32_16x16x32_bf16 v[60:63], v[88:91], v[188:191], v[60:63]
	v_mfma_f32_16x16x32_bf16 v[56:59], v[96:99], v[188:191], v[56:59]
	v_mfma_f32_16x16x32_bf16 v[52:55], v[88:91], v[196:199], v[52:55]
	v_mfma_f32_16x16x32_bf16 v[48:51], v[96:99], v[196:199], v[48:51]
	v_mfma_f32_16x16x32_bf16 v[44:47], v[88:91], v[204:207], v[44:47]
	v_mfma_f32_16x16x32_bf16 v[40:43], v[96:99], v[204:207], v[40:43]
	v_mfma_f32_16x16x32_bf16 v[36:39], v[88:91], v[212:215], v[36:39]
	v_mfma_f32_16x16x32_bf16 v[32:35], v[96:99], v[212:215], v[32:35]
	v_mfma_f32_16x16x32_bf16 v[60:63], v[92:95], v[192:195], v[60:63]
	v_mfma_f32_16x16x32_bf16 v[56:59], v[104:107], v[192:195], v[56:59]
	v_mfma_f32_16x16x32_bf16 v[52:55], v[92:95], v[200:203], v[52:55]
	v_mfma_f32_16x16x32_bf16 v[48:51], v[104:107], v[200:203], v[48:51]
	v_mfma_f32_16x16x32_bf16 v[44:47], v[92:95], v[208:211], v[44:47]
	v_mfma_f32_16x16x32_bf16 v[40:43], v[104:107], v[208:211], v[40:43]
	v_mfma_f32_16x16x32_bf16 v[36:39], v[92:95], v[228:231], v[36:39]
	v_mfma_f32_16x16x32_bf16 v[32:35], v[104:107], v[228:231], v[32:35]
	v_mfma_f32_16x16x32_bf16 v[140:143], v[160:163], v[188:191], v[140:143]
	v_mfma_f32_16x16x32_bf16 v[136:139], v[168:171], v[188:191], v[136:139]
	v_mfma_f32_16x16x32_bf16 v[132:135], v[160:163], v[196:199], v[132:135]
	v_mfma_f32_16x16x32_bf16 v[128:131], v[168:171], v[196:199], v[128:131]
	v_mfma_f32_16x16x32_bf16 v[124:127], v[160:163], v[204:207], v[124:127]
	v_mfma_f32_16x16x32_bf16 v[120:123], v[168:171], v[204:207], v[120:123]
	v_mfma_f32_16x16x32_bf16 v[116:119], v[160:163], v[212:215], v[116:119]
	v_mfma_f32_16x16x32_bf16 v[112:115], v[168:171], v[212:215], v[112:115]
	v_mfma_f32_16x16x32_bf16 v[140:143], v[164:167], v[192:195], v[140:143]
	v_mfma_f32_16x16x32_bf16 v[136:139], v[184:187], v[192:195], v[136:139]
	v_mfma_f32_16x16x32_bf16 v[132:135], v[164:167], v[200:203], v[132:135]
	v_mfma_f32_16x16x32_bf16 v[128:131], v[184:187], v[200:203], v[128:131]
	v_mfma_f32_16x16x32_bf16 v[124:127], v[164:167], v[208:211], v[124:127]
	v_mfma_f32_16x16x32_bf16 v[120:123], v[184:187], v[208:211], v[120:123]
	v_mfma_f32_16x16x32_bf16 v[116:119], v[164:167], v[228:231], v[116:119]
	v_mfma_f32_16x16x32_bf16 v[112:115], v[184:187], v[228:231], v[112:115]
	s_setprio 0
	s_barrier
	s_add_i32 s50, s50, s40
	v_lshl_add_u64 v[216:217], s[6:7], 0, v[148:149]
	s_mov_b32 m0, s50
	ds_read_b128 v[188:191], v227 offset:16384
	ds_read_b128 v[192:195], v227 offset:17408
	ds_read_b128 v[196:199], v227 offset:18432
	ds_read_b128 v[200:203], v227 offset:19456
	ds_read_b128 v[204:207], v227 offset:20480
	ds_read_b128 v[208:211], v227 offset:21504
	ds_read_b128 v[212:215], v227 offset:22528
	ds_read_b128 v[228:231], v227 offset:23552
	global_load_lds_dwordx4 v[216:217], off
	s_add_i32 m0, s50, 0x2000
	s_add_u32 s50, s6, 0x40000
	v_lshl_add_u64 v[232:233], s[6:7], 0, v[144:145]
	s_addc_u32 s51, s7, 0
	s_add_i32 s52, s52, s40
	global_load_lds_dwordx4 v[232:233], off
	v_lshl_add_u64 v[234:235], s[50:51], 0, v[148:149]
	s_mov_b32 m0, s52
	v_lshl_add_u64 v[236:237], s[28:29], 0, v[146:147]
	global_load_lds_dwordx4 v[234:235], off
	v_lshl_add_u64 v[234:235], s[50:51], 0, v[144:145]
	s_add_i32 m0, s52, 0x2000
	s_nop 0
	global_load_lds_dwordx4 v[234:235], off
	v_lshl_add_u64 v[234:235], s[28:29], 0, v[150:151]
	s_mov_b32 m0, s41
	s_nop 0
	global_load_lds_dwordx4 v[234:235], off
	s_mov_b32 m0, s42
	s_nop 0
	global_load_lds_dwordx4 v[236:237], off
	s_waitcnt vmcnt(8)
	s_waitcnt lgkmcnt(0)
	s_barrier
	s_setprio 1
	s_waitcnt lgkmcnt(0)
	v_mfma_f32_16x16x32_bf16 v[28:31], v[88:91], v[188:191], v[28:31]
	v_mfma_f32_16x16x32_bf16 v[24:27], v[96:99], v[188:191], v[24:27]
	v_mfma_f32_16x16x32_bf16 v[20:23], v[88:91], v[196:199], v[20:23]
	v_mfma_f32_16x16x32_bf16 v[16:19], v[96:99], v[196:199], v[16:19]
	v_mfma_f32_16x16x32_bf16 v[12:15], v[88:91], v[204:207], v[12:15]
	v_mfma_f32_16x16x32_bf16 v[8:11], v[96:99], v[204:207], v[8:11]
	v_mfma_f32_16x16x32_bf16 v[4:7], v[88:91], v[212:215], v[4:7]
	v_mfma_f32_16x16x32_bf16 v[0:3], v[96:99], v[212:215], v[0:3]
	v_mfma_f32_16x16x32_bf16 v[28:31], v[92:95], v[192:195], v[28:31]
	v_mfma_f32_16x16x32_bf16 v[24:27], v[104:107], v[192:195], v[24:27]
	v_mfma_f32_16x16x32_bf16 v[20:23], v[92:95], v[200:203], v[20:23]
	v_mfma_f32_16x16x32_bf16 v[16:19], v[104:107], v[200:203], v[16:19]
	v_mfma_f32_16x16x32_bf16 v[12:15], v[92:95], v[208:211], v[12:15]
	v_mfma_f32_16x16x32_bf16 v[8:11], v[104:107], v[208:211], v[8:11]
	v_mfma_f32_16x16x32_bf16 v[4:7], v[92:95], v[228:231], v[4:7]
	v_mfma_f32_16x16x32_bf16 v[0:3], v[104:107], v[228:231], v[0:3]
	v_mfma_f32_16x16x32_bf16 v[84:87], v[160:163], v[196:199], v[84:87]
	v_mfma_f32_16x16x32_bf16 v[80:83], v[168:171], v[196:199], v[80:83]
	v_mfma_f32_16x16x32_bf16 v[76:79], v[160:163], v[204:207], v[76:79]
	v_mfma_f32_16x16x32_bf16 v[72:75], v[168:171], v[204:207], v[72:75]
	v_mfma_f32_16x16x32_bf16 v[68:71], v[160:163], v[212:215], v[68:71]
	v_mfma_f32_16x16x32_bf16 v[64:67], v[168:171], v[212:215], v[64:67]
	v_mfma_f32_16x16x32_bf16 v[88:91], v[160:163], v[188:191], v[108:111]
	v_mfma_f32_16x16x32_bf16 v[92:95], v[168:171], v[188:191], v[100:103]
	v_mfma_f32_16x16x32_bf16 v[84:87], v[164:167], v[200:203], v[84:87]
	v_mfma_f32_16x16x32_bf16 v[80:83], v[184:187], v[200:203], v[80:83]
	v_mfma_f32_16x16x32_bf16 v[76:79], v[164:167], v[208:211], v[76:79]
	v_mfma_f32_16x16x32_bf16 v[72:75], v[184:187], v[208:211], v[72:75]
	v_mfma_f32_16x16x32_bf16 v[68:71], v[164:167], v[228:231], v[68:71]
	v_mfma_f32_16x16x32_bf16 v[64:67], v[184:187], v[228:231], v[64:67]
	v_mfma_f32_16x16x32_bf16 v[88:91], v[164:167], v[192:195], v[88:91]
	v_mfma_f32_16x16x32_bf16 v[92:95], v[184:187], v[192:195], v[92:95]
	s_setprio 0
	s_barrier
	s_add_i32 s50, 0, 0x18000
	s_add_i32 s51, 0, 0x1c000
	v_add_u32_e32 v108, s50, v220
	v_add_u32_e32 v174, s51, v220
	ds_read_b128 v[96:99], v108
	ds_read_b128 v[100:103], v108 offset:1024
	ds_read_b128 v[104:107], v108 offset:2048
	ds_read_b128 v[108:111], v108 offset:3072
	ds_read_b128 v[160:163], v174
	ds_read_b128 v[164:167], v174 offset:1024
	ds_read_b128 v[168:171], v174 offset:2048
	ds_read_b128 v[184:187], v174 offset:3072
	s_add_u32 s28, s28, 0x40000
	s_addc_u32 s29, s29, 0
	s_mov_b32 m0, s43
	v_lshl_add_u64 v[238:239], s[28:29], 0, v[150:151]
	ds_read_b128 v[188:191], v227 offset:32768
	ds_read_b128 v[192:195], v227 offset:33792
	ds_read_b128 v[196:199], v227 offset:34816
	ds_read_b128 v[200:203], v227 offset:35840
	ds_read_b128 v[204:207], v227 offset:36864
	ds_read_b128 v[208:211], v227 offset:37888
	ds_read_b128 v[212:215], v227 offset:38912
	ds_read_b128 v[228:231], v227 offset:39936
	global_load_lds_dwordx4 v[238:239], off
	v_lshl_add_u64 v[238:239], s[28:29], 0, v[146:147]
	s_mov_b32 m0, s44
	s_nop 0
	global_load_lds_dwordx4 v[238:239], off
	s_waitcnt vmcnt(8)
	s_waitcnt lgkmcnt(0)
	s_barrier
	s_setprio 1
	s_waitcnt lgkmcnt(0)
	v_mfma_f32_16x16x32_bf16 v[60:63], v[96:99], v[188:191], v[60:63]
	v_mfma_f32_16x16x32_bf16 v[56:59], v[104:107], v[188:191], v[56:59]
	v_mfma_f32_16x16x32_bf16 v[52:55], v[96:99], v[196:199], v[52:55]
	v_mfma_f32_16x16x32_bf16 v[48:51], v[104:107], v[196:199], v[48:51]
	v_mfma_f32_16x16x32_bf16 v[44:47], v[96:99], v[204:207], v[44:47]
	v_mfma_f32_16x16x32_bf16 v[40:43], v[104:107], v[204:207], v[40:43]
	v_mfma_f32_16x16x32_bf16 v[36:39], v[96:99], v[212:215], v[36:39]
	v_mfma_f32_16x16x32_bf16 v[32:35], v[104:107], v[212:215], v[32:35]
	v_mfma_f32_16x16x32_bf16 v[60:63], v[100:103], v[192:195], v[60:63]
	v_mfma_f32_16x16x32_bf16 v[56:59], v[108:111], v[192:195], v[56:59]
	v_mfma_f32_16x16x32_bf16 v[52:55], v[100:103], v[200:203], v[52:55]
	v_mfma_f32_16x16x32_bf16 v[48:51], v[108:111], v[200:203], v[48:51]
	v_mfma_f32_16x16x32_bf16 v[44:47], v[100:103], v[208:211], v[44:47]
	v_mfma_f32_16x16x32_bf16 v[40:43], v[108:111], v[208:211], v[40:43]
	v_mfma_f32_16x16x32_bf16 v[36:39], v[100:103], v[228:231], v[36:39]
	v_mfma_f32_16x16x32_bf16 v[32:35], v[108:111], v[228:231], v[32:35]
	v_mfma_f32_16x16x32_bf16 v[140:143], v[160:163], v[188:191], v[140:143]
	v_mfma_f32_16x16x32_bf16 v[136:139], v[168:171], v[188:191], v[136:139]
	v_mfma_f32_16x16x32_bf16 v[132:135], v[160:163], v[196:199], v[132:135]
	v_mfma_f32_16x16x32_bf16 v[128:131], v[168:171], v[196:199], v[128:131]
	v_mfma_f32_16x16x32_bf16 v[124:127], v[160:163], v[204:207], v[124:127]
	v_mfma_f32_16x16x32_bf16 v[120:123], v[168:171], v[204:207], v[120:123]
	v_mfma_f32_16x16x32_bf16 v[116:119], v[160:163], v[212:215], v[116:119]
	v_mfma_f32_16x16x32_bf16 v[112:115], v[168:171], v[212:215], v[112:115]
	v_mfma_f32_16x16x32_bf16 v[140:143], v[164:167], v[192:195], v[140:143]
	v_mfma_f32_16x16x32_bf16 v[136:139], v[184:187], v[192:195], v[136:139]
	v_mfma_f32_16x16x32_bf16 v[132:135], v[164:167], v[200:203], v[132:135]
	v_mfma_f32_16x16x32_bf16 v[128:131], v[184:187], v[200:203], v[128:131]
	v_mfma_f32_16x16x32_bf16 v[124:127], v[164:167], v[208:211], v[124:127]
	v_mfma_f32_16x16x32_bf16 v[120:123], v[184:187], v[208:211], v[120:123]
	v_mfma_f32_16x16x32_bf16 v[116:119], v[164:167], v[228:231], v[116:119]
	v_mfma_f32_16x16x32_bf16 v[112:115], v[184:187], v[228:231], v[112:115]
	s_setprio 0
	s_barrier
	s_add_i32 s28, s50, s40
	v_lshl_add_u64 v[216:217], v[216:217], 0, s[62:63]
	s_mov_b32 m0, s28
	ds_read_b128 v[188:191], v227 offset:49152
	ds_read_b128 v[192:195], v227 offset:50176
	ds_read_b128 v[196:199], v227 offset:51200
	ds_read_b128 v[200:203], v227 offset:52224
	ds_read_b128 v[204:207], v227 offset:53248
	ds_read_b128 v[208:211], v227 offset:54272
	ds_read_b128 v[212:215], v227 offset:55296
	ds_read_b128 v[228:231], v227 offset:56320
	global_load_lds_dwordx4 v[216:217], off
	s_add_i32 m0, s28, 0x2000
	s_add_u32 s6, s6, 0x40080
	v_lshl_add_u64 v[216:217], v[232:233], 0, s[62:63]
	s_addc_u32 s7, s7, 0
	s_add_i32 s28, s51, s40
	global_load_lds_dwordx4 v[216:217], off
	v_lshl_add_u64 v[216:217], s[6:7], 0, v[148:149]
	s_mov_b32 m0, s28
	s_nop 0
	global_load_lds_dwordx4 v[216:217], off
	v_lshl_add_u64 v[216:217], s[6:7], 0, v[144:145]
	s_add_i32 m0, s28, 0x2000
	s_nop 0
	global_load_lds_dwordx4 v[216:217], off
	v_lshl_add_u64 v[216:217], v[234:235], 0, s[62:63]
	s_mov_b32 m0, s45
	s_nop 0
	global_load_lds_dwordx4 v[216:217], off
	v_lshl_add_u64 v[216:217], v[236:237], 0, s[62:63]
	s_mov_b32 m0, s46
	s_nop 0
	global_load_lds_dwordx4 v[216:217], off
	s_waitcnt vmcnt(8)
	s_waitcnt lgkmcnt(0)
	s_barrier
	s_setprio 1
	s_waitcnt lgkmcnt(0)
	v_mfma_f32_16x16x32_bf16 v[28:31], v[96:99], v[188:191], v[28:31]
	v_mfma_f32_16x16x32_bf16 v[24:27], v[104:107], v[188:191], v[24:27]
	v_mfma_f32_16x16x32_bf16 v[20:23], v[96:99], v[196:199], v[20:23]
	v_mfma_f32_16x16x32_bf16 v[16:19], v[104:107], v[196:199], v[16:19]
	v_mfma_f32_16x16x32_bf16 v[12:15], v[96:99], v[204:207], v[12:15]
	v_mfma_f32_16x16x32_bf16 v[8:11], v[104:107], v[204:207], v[8:11]
	v_mfma_f32_16x16x32_bf16 v[4:7], v[96:99], v[212:215], v[4:7]
	v_mfma_f32_16x16x32_bf16 v[0:3], v[104:107], v[212:215], v[0:3]
	v_mfma_f32_16x16x32_bf16 v[28:31], v[100:103], v[192:195], v[28:31]
	v_mfma_f32_16x16x32_bf16 v[24:27], v[108:111], v[192:195], v[24:27]
	v_mfma_f32_16x16x32_bf16 v[20:23], v[100:103], v[200:203], v[20:23]
	v_mfma_f32_16x16x32_bf16 v[16:19], v[108:111], v[200:203], v[16:19]
	v_mfma_f32_16x16x32_bf16 v[12:15], v[100:103], v[208:211], v[12:15]
	v_mfma_f32_16x16x32_bf16 v[8:11], v[108:111], v[208:211], v[8:11]
	v_mfma_f32_16x16x32_bf16 v[4:7], v[100:103], v[228:231], v[4:7]
	v_mfma_f32_16x16x32_bf16 v[0:3], v[108:111], v[228:231], v[0:3]
	v_mfma_f32_16x16x32_bf16 v[88:91], v[160:163], v[188:191], v[88:91]
	v_mfma_f32_16x16x32_bf16 v[108:111], v[164:167], v[192:195], v[88:91]
	v_mfma_f32_16x16x32_bf16 v[88:91], v[168:171], v[188:191], v[92:95]
	v_mfma_f32_16x16x32_bf16 v[84:87], v[160:163], v[196:199], v[84:87]
	v_mfma_f32_16x16x32_bf16 v[80:83], v[168:171], v[196:199], v[80:83]
	v_mfma_f32_16x16x32_bf16 v[76:79], v[160:163], v[204:207], v[76:79]
	v_mfma_f32_16x16x32_bf16 v[72:75], v[168:171], v[204:207], v[72:75]
	v_mfma_f32_16x16x32_bf16 v[68:71], v[160:163], v[212:215], v[68:71]
	v_mfma_f32_16x16x32_bf16 v[64:67], v[168:171], v[212:215], v[64:67]
	v_mfma_f32_16x16x32_bf16 v[100:103], v[184:187], v[192:195], v[88:91]
	v_mfma_f32_16x16x32_bf16 v[84:87], v[164:167], v[200:203], v[84:87]
	v_mfma_f32_16x16x32_bf16 v[80:83], v[184:187], v[200:203], v[80:83]
	v_mfma_f32_16x16x32_bf16 v[76:79], v[164:167], v[208:211], v[76:79]
	v_mfma_f32_16x16x32_bf16 v[72:75], v[184:187], v[208:211], v[72:75]
	v_mfma_f32_16x16x32_bf16 v[68:71], v[164:167], v[228:231], v[68:71]
	v_mfma_f32_16x16x32_bf16 v[64:67], v[184:187], v[228:231], v[64:67]
	s_setprio 0
	s_barrier
	s_add_i32 s49, s49, 2
	s_add_u32 s0, s0, 0x100
	s_addc_u32 s1, s1, 0
	s_add_u32 s35, s35, 0x100
	s_addc_u32 s48, s48, 0
	s_cmp_gt_u32 s49, 13
	s_cbranch_scc0 .LBB0_163
	s_and_b64 vcc, exec, s[14:15]
	s_cbranch_vccz .LBB0_166
	s_barrier

.LBB0_944:
	s_add_u32 s24, s22, 0xfffc0080
	s_addc_u32 s25, s23, -1
	s_add_i32 s48, 0, 0x10000
	s_cmp_eq_u32 s47, 12
	s_cselect_b32 s27, s17, s25
	s_cselect_b32 s26, s43, s24
	s_cselect_b32 s25, s15, s46
	s_cselect_b32 s24, s44, s45
	s_add_i32 s50, 0, 0x14000
	v_add_u32_e32 v154, s48, v147
	v_add_u32_e32 v170, s50, v147
	ds_read_b128 v[128:131], v154
	ds_read_b128 v[142:145], v154 offset:1024
	ds_read_b128 v[150:153], v154 offset:2048
	ds_read_b128 v[154:157], v154 offset:3072
	ds_read_b128 v[158:161], v170
	ds_read_b128 v[162:165], v170 offset:1024
	ds_read_b128 v[166:169], v170 offset:2048
	ds_read_b128 v[184:187], v170 offset:3072
	v_lshl_add_u64 v[170:171], s[22:23], 0, v[138:139]
	s_add_i32 m0, s35, 0xc000
	ds_read_b128 v[188:191], v149
	ds_read_b128 v[192:195], v149 offset:1024
	ds_read_b128 v[196:199], v149 offset:2048
	ds_read_b128 v[200:203], v149 offset:3072
	ds_read_b128 v[204:207], v149 offset:4096
	ds_read_b128 v[208:211], v149 offset:5120
	ds_read_b128 v[212:215], v149 offset:6144
	ds_read_b128 v[228:231], v149 offset:7168
	global_load_lds_dwordx4 v[170:171], off
	v_lshl_add_u64 v[170:171], s[22:23], 0, v[140:141]
	s_add_i32 m0, s35, 0xe000
	s_nop 0
	global_load_lds_dwordx4 v[170:171], off
	s_waitcnt vmcnt(8)
	s_waitcnt lgkmcnt(0)
	s_barrier
	s_setprio 1
	s_waitcnt lgkmcnt(0)
	v_mfma_f32_16x16x32_bf16 v[124:127], v[128:131], v[188:191], v[124:127]
	v_mfma_f32_16x16x32_bf16 v[120:123], v[150:153], v[188:191], v[120:123]
	v_mfma_f32_16x16x32_bf16 v[108:111], v[128:131], v[196:199], v[108:111]
	v_mfma_f32_16x16x32_bf16 v[104:107], v[150:153], v[196:199], v[104:107]
	v_mfma_f32_16x16x32_bf16 v[92:95], v[128:131], v[204:207], v[92:95]
	v_mfma_f32_16x16x32_bf16 v[88:91], v[150:153], v[204:207], v[88:91]
	v_mfma_f32_16x16x32_bf16 v[76:79], v[128:131], v[212:215], v[76:79]
	v_mfma_f32_16x16x32_bf16 v[72:75], v[150:153], v[212:215], v[72:75]
	v_mfma_f32_16x16x32_bf16 v[124:127], v[142:145], v[192:195], v[124:127]
	v_mfma_f32_16x16x32_bf16 v[120:123], v[154:157], v[192:195], v[120:123]
	v_mfma_f32_16x16x32_bf16 v[108:111], v[142:145], v[200:203], v[108:111]
	v_mfma_f32_16x16x32_bf16 v[104:107], v[154:157], v[200:203], v[104:107]
	v_mfma_f32_16x16x32_bf16 v[92:95], v[142:145], v[208:211], v[92:95]
	v_mfma_f32_16x16x32_bf16 v[88:91], v[154:157], v[208:211], v[88:91]
	v_mfma_f32_16x16x32_bf16 v[76:79], v[142:145], v[228:231], v[76:79]
	v_mfma_f32_16x16x32_bf16 v[72:75], v[154:157], v[228:231], v[72:75]
	v_mfma_f32_16x16x32_bf16 v[116:119], v[158:161], v[188:191], v[116:119]
	v_mfma_f32_16x16x32_bf16 v[112:115], v[166:169], v[188:191], v[112:115]
	v_mfma_f32_16x16x32_bf16 v[100:103], v[158:161], v[196:199], v[100:103]
	v_mfma_f32_16x16x32_bf16 v[96:99], v[166:169], v[196:199], v[96:99]
	v_mfma_f32_16x16x32_bf16 v[84:87], v[158:161], v[204:207], v[84:87]
	v_mfma_f32_16x16x32_bf16 v[80:83], v[166:169], v[204:207], v[80:83]
	v_mfma_f32_16x16x32_bf16 v[68:71], v[158:161], v[212:215], v[68:71]
	v_mfma_f32_16x16x32_bf16 v[64:67], v[166:169], v[212:215], v[64:67]
	v_mfma_f32_16x16x32_bf16 v[116:119], v[162:165], v[192:195], v[116:119]
	v_mfma_f32_16x16x32_bf16 v[112:115], v[184:187], v[192:195], v[112:115]
	v_mfma_f32_16x16x32_bf16 v[100:103], v[162:165], v[200:203], v[100:103]
	v_mfma_f32_16x16x32_bf16 v[96:99], v[184:187], v[200:203], v[96:99]
	v_mfma_f32_16x16x32_bf16 v[84:87], v[162:165], v[208:211], v[84:87]
	v_mfma_f32_16x16x32_bf16 v[80:83], v[184:187], v[208:211], v[80:83]
	v_mfma_f32_16x16x32_bf16 v[68:71], v[162:165], v[228:231], v[68:71]
	v_mfma_f32_16x16x32_bf16 v[64:67], v[184:187], v[228:231], v[64:67]
	s_setprio 0
	s_barrier
	s_add_i32 s48, s48, s34
	v_lshl_add_u64 v[170:171], s[24:25], 0, v[174:175]
	s_mov_b32 m0, s48
	ds_read_b128 v[188:191], v149 offset:16384
	ds_read_b128 v[192:195], v149 offset:17408
	ds_read_b128 v[196:199], v149 offset:18432
	ds_read_b128 v[200:203], v149 offset:19456
	ds_read_b128 v[204:207], v149 offset:20480
	ds_read_b128 v[208:211], v149 offset:21504
	ds_read_b128 v[212:215], v149 offset:22528
	ds_read_b128 v[228:231], v149 offset:23552
	global_load_lds_dwordx4 v[170:171], off
	s_add_i32 m0, s48, 0x2000
	s_add_u32 s48, s24, 0x40000
	v_lshl_add_u64 v[216:217], s[24:25], 0, v[132:133]
	s_addc_u32 s49, s25, 0
	s_add_i32 s50, s50, s34
	global_load_lds_dwordx4 v[216:217], off
	v_lshl_add_u64 v[220:221], s[48:49], 0, v[174:175]
	s_mov_b32 m0, s50
	v_lshl_add_u64 v[232:233], s[26:27], 0, v[134:135]
	global_load_lds_dwordx4 v[220:221], off
	v_lshl_add_u64 v[220:221], s[48:49], 0, v[132:133]
	s_add_i32 m0, s50, 0x2000
	s_nop 0
	global_load_lds_dwordx4 v[220:221], off
	v_lshl_add_u64 v[220:221], s[26:27], 0, v[136:137]
	s_mov_b32 m0, s35
	s_nop 0
	global_load_lds_dwordx4 v[220:221], off
	s_mov_b32 m0, s36
	s_nop 0
	global_load_lds_dwordx4 v[232:233], off
	s_waitcnt vmcnt(8)
	s_waitcnt lgkmcnt(0)
	s_barrier
	s_setprio 1
	s_waitcnt lgkmcnt(0)
	v_mfma_f32_16x16x32_bf16 v[60:63], v[128:131], v[188:191], v[60:63]
	v_mfma_f32_16x16x32_bf16 v[56:59], v[150:153], v[188:191], v[56:59]
	v_mfma_f32_16x16x32_bf16 v[44:47], v[128:131], v[196:199], v[44:47]
	v_mfma_f32_16x16x32_bf16 v[40:43], v[150:153], v[196:199], v[40:43]
	v_mfma_f32_16x16x32_bf16 v[28:31], v[128:131], v[204:207], v[28:31]
	v_mfma_f32_16x16x32_bf16 v[24:27], v[150:153], v[204:207], v[24:27]
	v_mfma_f32_16x16x32_bf16 v[12:15], v[128:131], v[212:215], v[12:15]
	v_mfma_f32_16x16x32_bf16 v[8:11], v[150:153], v[212:215], v[8:11]
	v_mfma_f32_16x16x32_bf16 v[60:63], v[142:145], v[192:195], v[60:63]
	v_mfma_f32_16x16x32_bf16 v[56:59], v[154:157], v[192:195], v[56:59]
	v_mfma_f32_16x16x32_bf16 v[44:47], v[142:145], v[200:203], v[44:47]
	v_mfma_f32_16x16x32_bf16 v[40:43], v[154:157], v[200:203], v[40:43]
	v_mfma_f32_16x16x32_bf16 v[28:31], v[142:145], v[208:211], v[28:31]
	v_mfma_f32_16x16x32_bf16 v[24:27], v[154:157], v[208:211], v[24:27]
	v_mfma_f32_16x16x32_bf16 v[12:15], v[142:145], v[228:231], v[12:15]
	v_mfma_f32_16x16x32_bf16 v[8:11], v[154:157], v[228:231], v[8:11]
	v_mfma_f32_16x16x32_bf16 v[52:55], v[158:161], v[188:191], v[52:55]
	v_mfma_f32_16x16x32_bf16 v[48:51], v[166:169], v[188:191], v[48:51]
	v_mfma_f32_16x16x32_bf16 v[36:39], v[158:161], v[196:199], v[36:39]
	v_mfma_f32_16x16x32_bf16 v[32:35], v[166:169], v[196:199], v[32:35]
	v_mfma_f32_16x16x32_bf16 v[20:23], v[158:161], v[204:207], v[20:23]
	v_mfma_f32_16x16x32_bf16 v[16:19], v[166:169], v[204:207], v[16:19]
	v_mfma_f32_16x16x32_bf16 v[4:7], v[158:161], v[212:215], v[4:7]
	v_mfma_f32_16x16x32_bf16 v[0:3], v[166:169], v[212:215], v[0:3]
	v_mfma_f32_16x16x32_bf16 v[52:55], v[162:165], v[192:195], v[52:55]
	v_mfma_f32_16x16x32_bf16 v[48:51], v[184:187], v[192:195], v[48:51]
	v_mfma_f32_16x16x32_bf16 v[36:39], v[162:165], v[200:203], v[36:39]
	v_mfma_f32_16x16x32_bf16 v[32:35], v[184:187], v[200:203], v[32:35]
	v_mfma_f32_16x16x32_bf16 v[20:23], v[162:165], v[208:211], v[20:23]
	v_mfma_f32_16x16x32_bf16 v[16:19], v[184:187], v[208:211], v[16:19]
	v_mfma_f32_16x16x32_bf16 v[4:7], v[162:165], v[228:231], v[4:7]
	v_mfma_f32_16x16x32_bf16 v[0:3], v[184:187], v[228:231], v[0:3]
	s_setprio 0
	s_barrier
	s_add_i32 s48, 0, 0x18000
	s_add_i32 s49, 0, 0x1c000
	v_add_u32_e32 v154, s48, v147
	v_add_u32_e32 v184, s49, v147
	ds_read_b128 v[128:131], v154
	ds_read_b128 v[142:145], v154 offset:1024
	ds_read_b128 v[150:153], v154 offset:2048
	ds_read_b128 v[154:157], v154 offset:3072
	ds_read_b128 v[158:161], v184
	ds_read_b128 v[162:165], v184 offset:1024
	ds_read_b128 v[166:169], v184 offset:2048
	ds_read_b128 v[184:187], v184 offset:3072
	s_add_u32 s26, s26, 0x40000
	s_addc_u32 s27, s27, 0
	s_mov_b32 m0, s37
	v_lshl_add_u64 v[234:235], s[26:27], 0, v[136:137]
	ds_read_b128 v[188:191], v149 offset:32768
	ds_read_b128 v[192:195], v149 offset:33792
	ds_read_b128 v[196:199], v149 offset:34816
	ds_read_b128 v[200:203], v149 offset:35840
	ds_read_b128 v[204:207], v149 offset:36864
	ds_read_b128 v[208:211], v149 offset:37888
	ds_read_b128 v[212:215], v149 offset:38912
	ds_read_b128 v[228:231], v149 offset:39936
	global_load_lds_dwordx4 v[234:235], off
	v_lshl_add_u64 v[234:235], s[26:27], 0, v[134:135]
	s_mov_b32 m0, s38
	s_nop 0
	global_load_lds_dwordx4 v[234:235], off
	s_waitcnt vmcnt(8)
	s_waitcnt lgkmcnt(0)
	s_barrier
	s_setprio 1
	s_waitcnt lgkmcnt(0)
	v_mfma_f32_16x16x32_bf16 v[124:127], v[128:131], v[188:191], v[124:127]
	v_mfma_f32_16x16x32_bf16 v[120:123], v[150:153], v[188:191], v[120:123]
	v_mfma_f32_16x16x32_bf16 v[108:111], v[128:131], v[196:199], v[108:111]
	v_mfma_f32_16x16x32_bf16 v[104:107], v[150:153], v[196:199], v[104:107]
	v_mfma_f32_16x16x32_bf16 v[92:95], v[128:131], v[204:207], v[92:95]
	v_mfma_f32_16x16x32_bf16 v[88:91], v[150:153], v[204:207], v[88:91]
	v_mfma_f32_16x16x32_bf16 v[76:79], v[128:131], v[212:215], v[76:79]
	v_mfma_f32_16x16x32_bf16 v[72:75], v[150:153], v[212:215], v[72:75]
	v_mfma_f32_16x16x32_bf16 v[124:127], v[142:145], v[192:195], v[124:127]
	v_mfma_f32_16x16x32_bf16 v[120:123], v[154:157], v[192:195], v[120:123]
	v_mfma_f32_16x16x32_bf16 v[108:111], v[142:145], v[200:203], v[108:111]
	v_mfma_f32_16x16x32_bf16 v[104:107], v[154:157], v[200:203], v[104:107]
	v_mfma_f32_16x16x32_bf16 v[92:95], v[142:145], v[208:211], v[92:95]
	v_mfma_f32_16x16x32_bf16 v[88:91], v[154:157], v[208:211], v[88:91]
	v_mfma_f32_16x16x32_bf16 v[76:79], v[142:145], v[228:231], v[76:79]
	v_mfma_f32_16x16x32_bf16 v[72:75], v[154:157], v[228:231], v[72:75]
	v_mfma_f32_16x16x32_bf16 v[116:119], v[158:161], v[188:191], v[116:119]
	v_mfma_f32_16x16x32_bf16 v[112:115], v[166:169], v[188:191], v[112:115]
	v_mfma_f32_16x16x32_bf16 v[100:103], v[158:161], v[196:199], v[100:103]
	v_mfma_f32_16x16x32_bf16 v[96:99], v[166:169], v[196:199], v[96:99]
	v_mfma_f32_16x16x32_bf16 v[84:87], v[158:161], v[204:207], v[84:87]
	v_mfma_f32_16x16x32_bf16 v[80:83], v[166:169], v[204:207], v[80:83]
	v_mfma_f32_16x16x32_bf16 v[68:71], v[158:161], v[212:215], v[68:71]
	v_mfma_f32_16x16x32_bf16 v[64:67], v[166:169], v[212:215], v[64:67]
	v_mfma_f32_16x16x32_bf16 v[116:119], v[162:165], v[192:195], v[116:119]
	v_mfma_f32_16x16x32_bf16 v[112:115], v[184:187], v[192:195], v[112:115]
	v_mfma_f32_16x16x32_bf16 v[100:103], v[162:165], v[200:203], v[100:103]
	v_mfma_f32_16x16x32_bf16 v[96:99], v[184:187], v[200:203], v[96:99]
	v_mfma_f32_16x16x32_bf16 v[84:87], v[162:165], v[208:211], v[84:87]
	v_mfma_f32_16x16x32_bf16 v[80:83], v[184:187], v[208:211], v[80:83]
	v_mfma_f32_16x16x32_bf16 v[68:71], v[162:165], v[228:231], v[68:71]
	v_mfma_f32_16x16x32_bf16 v[64:67], v[184:187], v[228:231], v[64:67]
	s_setprio 0
	s_barrier
	s_add_i32 s26, s48, s34
	v_lshl_add_u64 v[170:171], v[170:171], 0, s[62:63]
	s_mov_b32 m0, s26
	ds_read_b128 v[188:191], v149 offset:49152
	ds_read_b128 v[192:195], v149 offset:50176
	ds_read_b128 v[196:199], v149 offset:51200
	ds_read_b128 v[200:203], v149 offset:52224
	ds_read_b128 v[204:207], v149 offset:53248
	ds_read_b128 v[208:211], v149 offset:54272
	ds_read_b128 v[212:215], v149 offset:55296
	ds_read_b128 v[228:231], v149 offset:56320
	global_load_lds_dwordx4 v[170:171], off
	s_add_i32 m0, s26, 0x2000
	s_add_u32 s24, s24, 0x40080
	v_lshl_add_u64 v[170:171], v[216:217], 0, s[62:63]
	s_addc_u32 s25, s25, 0
	s_add_i32 s26, s49, s34
	global_load_lds_dwordx4 v[170:171], off
	v_lshl_add_u64 v[170:171], s[24:25], 0, v[174:175]
	s_mov_b32 m0, s26
	s_nop 0
	global_load_lds_dwordx4 v[170:171], off
	v_lshl_add_u64 v[170:171], s[24:25], 0, v[132:133]
	s_add_i32 m0, s26, 0x2000
	s_nop 0
	global_load_lds_dwordx4 v[170:171], off
	v_lshl_add_u64 v[170:171], v[220:221], 0, s[62:63]
	s_mov_b32 m0, s39
	s_nop 0
	global_load_lds_dwordx4 v[170:171], off
	v_lshl_add_u64 v[170:171], v[232:233], 0, s[62:63]
	s_mov_b32 m0, s40
	s_nop 0
	global_load_lds_dwordx4 v[170:171], off
	s_waitcnt vmcnt(8)
	s_waitcnt lgkmcnt(0)
	s_barrier
	s_setprio 1
	s_waitcnt lgkmcnt(0)
	v_mfma_f32_16x16x32_bf16 v[60:63], v[128:131], v[188:191], v[60:63]
	v_mfma_f32_16x16x32_bf16 v[56:59], v[150:153], v[188:191], v[56:59]
	v_mfma_f32_16x16x32_bf16 v[44:47], v[128:131], v[196:199], v[44:47]
	v_mfma_f32_16x16x32_bf16 v[40:43], v[150:153], v[196:199], v[40:43]
	v_mfma_f32_16x16x32_bf16 v[28:31], v[128:131], v[204:207], v[28:31]
	v_mfma_f32_16x16x32_bf16 v[24:27], v[150:153], v[204:207], v[24:27]
	v_mfma_f32_16x16x32_bf16 v[12:15], v[128:131], v[212:215], v[12:15]
	v_mfma_f32_16x16x32_bf16 v[8:11], v[150:153], v[212:215], v[8:11]
	v_mfma_f32_16x16x32_bf16 v[60:63], v[142:145], v[192:195], v[60:63]
	v_mfma_f32_16x16x32_bf16 v[56:59], v[154:157], v[192:195], v[56:59]
	v_mfma_f32_16x16x32_bf16 v[44:47], v[142:145], v[200:203], v[44:47]
	v_mfma_f32_16x16x32_bf16 v[40:43], v[154:157], v[200:203], v[40:43]
	v_mfma_f32_16x16x32_bf16 v[28:31], v[142:145], v[208:211], v[28:31]
	v_mfma_f32_16x16x32_bf16 v[24:27], v[154:157], v[208:211], v[24:27]
	v_mfma_f32_16x16x32_bf16 v[12:15], v[142:145], v[228:231], v[12:15]
	v_mfma_f32_16x16x32_bf16 v[8:11], v[154:157], v[228:231], v[8:11]
	v_mfma_f32_16x16x32_bf16 v[52:55], v[158:161], v[188:191], v[52:55]
	v_mfma_f32_16x16x32_bf16 v[48:51], v[166:169], v[188:191], v[48:51]
	v_mfma_f32_16x16x32_bf16 v[36:39], v[158:161], v[196:199], v[36:39]
	v_mfma_f32_16x16x32_bf16 v[32:35], v[166:169], v[196:199], v[32:35]
	v_mfma_f32_16x16x32_bf16 v[20:23], v[158:161], v[204:207], v[20:23]
	v_mfma_f32_16x16x32_bf16 v[16:19], v[166:169], v[204:207], v[16:19]
	v_mfma_f32_16x16x32_bf16 v[4:7], v[158:161], v[212:215], v[4:7]
	v_mfma_f32_16x16x32_bf16 v[0:3], v[166:169], v[212:215], v[0:3]
	v_mfma_f32_16x16x32_bf16 v[52:55], v[162:165], v[192:195], v[52:55]
	v_mfma_f32_16x16x32_bf16 v[48:51], v[184:187], v[192:195], v[48:51]
	v_mfma_f32_16x16x32_bf16 v[36:39], v[162:165], v[200:203], v[36:39]
	v_mfma_f32_16x16x32_bf16 v[32:35], v[184:187], v[200:203], v[32:35]
	v_mfma_f32_16x16x32_bf16 v[20:23], v[162:165], v[208:211], v[20:23]
	v_mfma_f32_16x16x32_bf16 v[16:19], v[184:187], v[208:211], v[16:19]
	v_mfma_f32_16x16x32_bf16 v[4:7], v[162:165], v[228:231], v[4:7]
	v_mfma_f32_16x16x32_bf16 v[0:3], v[184:187], v[228:231], v[0:3]
	s_setprio 0
	s_barrier
	s_add_i32 s47, s47, 2
	s_add_u32 s22, s22, 0x100
	s_addc_u32 s23, s23, 0
	s_add_u32 s45, s45, 0x100
	s_addc_u32 s46, s46, 0
	s_cmp_gt_u32 s47, 13
	s_cbranch_scc0 .LBB0_944
	s_and_b64 vcc, exec, s[12:13]
	s_cbranch_vccz .LBB0_947
	s_barrier

.LBB0_964:
	s_add_u32 s26, s24, 0xfffc0080
	s_addc_u32 s27, s25, -1
	s_add_i32 s50, 0, 0x10000
	s_cmp_eq_u32 s49, 12
	s_cselect_b32 s29, s19, s27
	s_cselect_b32 s28, s45, s26
	s_cselect_b32 s27, s17, s48
	s_cselect_b32 s26, s46, s47
	s_add_i32 s52, 0, 0x14000
	v_add_u32_e32 v140, s50, v163
	v_add_u32_e32 v170, s52, v163
	ds_read_b128 v[128:131], v140
	ds_read_b128 v[132:135], v140 offset:1024
	ds_read_b128 v[136:139], v140 offset:2048
	ds_read_b128 v[140:143], v140 offset:3072
	ds_read_b128 v[154:157], v170
	ds_read_b128 v[158:161], v170 offset:1024
	ds_read_b128 v[166:169], v170 offset:2048
	ds_read_b128 v[184:187], v170 offset:3072
	v_lshl_add_u64 v[170:171], s[24:25], 0, v[150:151]
	s_add_i32 m0, s37, 0xc000
	ds_read_b128 v[188:191], v165
	ds_read_b128 v[192:195], v165 offset:1024
	ds_read_b128 v[196:199], v165 offset:2048
	ds_read_b128 v[200:203], v165 offset:3072
	ds_read_b128 v[204:207], v165 offset:4096
	ds_read_b128 v[208:211], v165 offset:5120
	ds_read_b128 v[212:215], v165 offset:6144
	ds_read_b128 v[228:231], v165 offset:7168
	global_load_lds_dwordx4 v[170:171], off
	v_lshl_add_u64 v[170:171], s[24:25], 0, v[152:153]
	s_add_i32 m0, s37, 0xe000
	s_nop 0
	global_load_lds_dwordx4 v[170:171], off
	s_waitcnt vmcnt(8)
	s_waitcnt lgkmcnt(0)
	s_barrier
	s_setprio 1
	s_waitcnt lgkmcnt(0)
	v_mfma_f32_16x16x32_bf16 v[124:127], v[128:131], v[188:191], v[124:127]
	v_mfma_f32_16x16x32_bf16 v[120:123], v[136:139], v[188:191], v[120:123]
	v_mfma_f32_16x16x32_bf16 v[108:111], v[128:131], v[196:199], v[108:111]
	v_mfma_f32_16x16x32_bf16 v[104:107], v[136:139], v[196:199], v[104:107]
	v_mfma_f32_16x16x32_bf16 v[92:95], v[128:131], v[204:207], v[92:95]
	v_mfma_f32_16x16x32_bf16 v[88:91], v[136:139], v[204:207], v[88:91]
	v_mfma_f32_16x16x32_bf16 v[76:79], v[128:131], v[212:215], v[76:79]
	v_mfma_f32_16x16x32_bf16 v[72:75], v[136:139], v[212:215], v[72:75]
	v_mfma_f32_16x16x32_bf16 v[124:127], v[132:135], v[192:195], v[124:127]
	v_mfma_f32_16x16x32_bf16 v[120:123], v[140:143], v[192:195], v[120:123]
	v_mfma_f32_16x16x32_bf16 v[108:111], v[132:135], v[200:203], v[108:111]
	v_mfma_f32_16x16x32_bf16 v[104:107], v[140:143], v[200:203], v[104:107]
	v_mfma_f32_16x16x32_bf16 v[92:95], v[132:135], v[208:211], v[92:95]
	v_mfma_f32_16x16x32_bf16 v[88:91], v[140:143], v[208:211], v[88:91]
	v_mfma_f32_16x16x32_bf16 v[76:79], v[132:135], v[228:231], v[76:79]
	v_mfma_f32_16x16x32_bf16 v[72:75], v[140:143], v[228:231], v[72:75]
	v_mfma_f32_16x16x32_bf16 v[116:119], v[154:157], v[188:191], v[116:119]
	v_mfma_f32_16x16x32_bf16 v[112:115], v[166:169], v[188:191], v[112:115]
	v_mfma_f32_16x16x32_bf16 v[100:103], v[154:157], v[196:199], v[100:103]
	v_mfma_f32_16x16x32_bf16 v[96:99], v[166:169], v[196:199], v[96:99]
	v_mfma_f32_16x16x32_bf16 v[84:87], v[154:157], v[204:207], v[84:87]
	v_mfma_f32_16x16x32_bf16 v[80:83], v[166:169], v[204:207], v[80:83]
	v_mfma_f32_16x16x32_bf16 v[68:71], v[154:157], v[212:215], v[68:71]
	v_mfma_f32_16x16x32_bf16 v[64:67], v[166:169], v[212:215], v[64:67]
	v_mfma_f32_16x16x32_bf16 v[116:119], v[158:161], v[192:195], v[116:119]
	v_mfma_f32_16x16x32_bf16 v[112:115], v[184:187], v[192:195], v[112:115]
	v_mfma_f32_16x16x32_bf16 v[100:103], v[158:161], v[200:203], v[100:103]
	v_mfma_f32_16x16x32_bf16 v[96:99], v[184:187], v[200:203], v[96:99]
	v_mfma_f32_16x16x32_bf16 v[84:87], v[158:161], v[208:211], v[84:87]
	v_mfma_f32_16x16x32_bf16 v[80:83], v[184:187], v[208:211], v[80:83]
	v_mfma_f32_16x16x32_bf16 v[68:71], v[158:161], v[228:231], v[68:71]
	v_mfma_f32_16x16x32_bf16 v[64:67], v[184:187], v[228:231], v[64:67]
	s_setprio 0
	s_barrier
	s_add_i32 s50, s50, s36
	v_lshl_add_u64 v[170:171], s[26:27], 0, v[174:175]
	s_mov_b32 m0, s50
	ds_read_b128 v[188:191], v165 offset:16384
	ds_read_b128 v[192:195], v165 offset:17408
	ds_read_b128 v[196:199], v165 offset:18432
	ds_read_b128 v[200:203], v165 offset:19456
	ds_read_b128 v[204:207], v165 offset:20480
	ds_read_b128 v[208:211], v165 offset:21504
	ds_read_b128 v[212:215], v165 offset:22528
	ds_read_b128 v[228:231], v165 offset:23552
	global_load_lds_dwordx4 v[170:171], off
	s_add_i32 m0, s50, 0x2000
	s_add_u32 s50, s26, 0x40000
	v_lshl_add_u64 v[216:217], s[26:27], 0, v[144:145]
	s_addc_u32 s51, s27, 0
	s_add_i32 s52, s52, s36
	global_load_lds_dwordx4 v[216:217], off
	v_lshl_add_u64 v[220:221], s[50:51], 0, v[174:175]
	s_mov_b32 m0, s52
	v_lshl_add_u64 v[232:233], s[28:29], 0, v[146:147]
	global_load_lds_dwordx4 v[220:221], off
	v_lshl_add_u64 v[220:221], s[50:51], 0, v[144:145]
	s_add_i32 m0, s52, 0x2000
	s_nop 0
	global_load_lds_dwordx4 v[220:221], off
	v_lshl_add_u64 v[220:221], s[28:29], 0, v[148:149]
	s_mov_b32 m0, s37
	s_nop 0
	global_load_lds_dwordx4 v[220:221], off
	s_mov_b32 m0, s38
	s_nop 0
	global_load_lds_dwordx4 v[232:233], off
	s_waitcnt vmcnt(8)
	s_waitcnt lgkmcnt(0)
	s_barrier
	s_setprio 1
	s_waitcnt lgkmcnt(0)
	v_mfma_f32_16x16x32_bf16 v[60:63], v[128:131], v[188:191], v[60:63]
	v_mfma_f32_16x16x32_bf16 v[56:59], v[136:139], v[188:191], v[56:59]
	v_mfma_f32_16x16x32_bf16 v[44:47], v[128:131], v[196:199], v[44:47]
	v_mfma_f32_16x16x32_bf16 v[40:43], v[136:139], v[196:199], v[40:43]
	v_mfma_f32_16x16x32_bf16 v[28:31], v[128:131], v[204:207], v[28:31]
	v_mfma_f32_16x16x32_bf16 v[24:27], v[136:139], v[204:207], v[24:27]
	v_mfma_f32_16x16x32_bf16 v[12:15], v[128:131], v[212:215], v[12:15]
	v_mfma_f32_16x16x32_bf16 v[8:11], v[136:139], v[212:215], v[8:11]
	v_mfma_f32_16x16x32_bf16 v[60:63], v[132:135], v[192:195], v[60:63]
	v_mfma_f32_16x16x32_bf16 v[56:59], v[140:143], v[192:195], v[56:59]
	v_mfma_f32_16x16x32_bf16 v[44:47], v[132:135], v[200:203], v[44:47]
	v_mfma_f32_16x16x32_bf16 v[40:43], v[140:143], v[200:203], v[40:43]
	v_mfma_f32_16x16x32_bf16 v[28:31], v[132:135], v[208:211], v[28:31]
	v_mfma_f32_16x16x32_bf16 v[24:27], v[140:143], v[208:211], v[24:27]
	v_mfma_f32_16x16x32_bf16 v[12:15], v[132:135], v[228:231], v[12:15]
	v_mfma_f32_16x16x32_bf16 v[8:11], v[140:143], v[228:231], v[8:11]
	v_mfma_f32_16x16x32_bf16 v[52:55], v[154:157], v[188:191], v[52:55]
	v_mfma_f32_16x16x32_bf16 v[48:51], v[166:169], v[188:191], v[48:51]
	v_mfma_f32_16x16x32_bf16 v[36:39], v[154:157], v[196:199], v[36:39]
	v_mfma_f32_16x16x32_bf16 v[32:35], v[166:169], v[196:199], v[32:35]
	v_mfma_f32_16x16x32_bf16 v[20:23], v[154:157], v[204:207], v[20:23]
	v_mfma_f32_16x16x32_bf16 v[16:19], v[166:169], v[204:207], v[16:19]
	v_mfma_f32_16x16x32_bf16 v[4:7], v[154:157], v[212:215], v[4:7]
	v_mfma_f32_16x16x32_bf16 v[0:3], v[166:169], v[212:215], v[0:3]
	v_mfma_f32_16x16x32_bf16 v[52:55], v[158:161], v[192:195], v[52:55]
	v_mfma_f32_16x16x32_bf16 v[48:51], v[184:187], v[192:195], v[48:51]
	v_mfma_f32_16x16x32_bf16 v[36:39], v[158:161], v[200:203], v[36:39]
	v_mfma_f32_16x16x32_bf16 v[32:35], v[184:187], v[200:203], v[32:35]
	v_mfma_f32_16x16x32_bf16 v[20:23], v[158:161], v[208:211], v[20:23]
	v_mfma_f32_16x16x32_bf16 v[16:19], v[184:187], v[208:211], v[16:19]
	v_mfma_f32_16x16x32_bf16 v[4:7], v[158:161], v[228:231], v[4:7]
	v_mfma_f32_16x16x32_bf16 v[0:3], v[184:187], v[228:231], v[0:3]
	s_setprio 0
	s_barrier
	s_add_i32 s50, 0, 0x18000
	s_add_i32 s51, 0, 0x1c000
	v_add_u32_e32 v140, s50, v163
	v_add_u32_e32 v184, s51, v163
	ds_read_b128 v[128:131], v140
	ds_read_b128 v[132:135], v140 offset:1024
	ds_read_b128 v[136:139], v140 offset:2048
	ds_read_b128 v[140:143], v140 offset:3072
	ds_read_b128 v[154:157], v184
	ds_read_b128 v[158:161], v184 offset:1024
	ds_read_b128 v[166:169], v184 offset:2048
	ds_read_b128 v[184:187], v184 offset:3072
	s_add_u32 s28, s28, 0x40000
	s_addc_u32 s29, s29, 0
	s_mov_b32 m0, s39
	v_lshl_add_u64 v[234:235], s[28:29], 0, v[148:149]
	ds_read_b128 v[188:191], v165 offset:32768
	ds_read_b128 v[192:195], v165 offset:33792
	ds_read_b128 v[196:199], v165 offset:34816
	ds_read_b128 v[200:203], v165 offset:35840
	ds_read_b128 v[204:207], v165 offset:36864
	ds_read_b128 v[208:211], v165 offset:37888
	ds_read_b128 v[212:215], v165 offset:38912
	ds_read_b128 v[228:231], v165 offset:39936
	global_load_lds_dwordx4 v[234:235], off
	v_lshl_add_u64 v[234:235], s[28:29], 0, v[146:147]
	s_mov_b32 m0, s40
	s_nop 0
	global_load_lds_dwordx4 v[234:235], off
	s_waitcnt vmcnt(8)
	s_waitcnt lgkmcnt(0)
	s_barrier
	s_setprio 1
	s_waitcnt lgkmcnt(0)
	v_mfma_f32_16x16x32_bf16 v[124:127], v[128:131], v[188:191], v[124:127]
	v_mfma_f32_16x16x32_bf16 v[120:123], v[136:139], v[188:191], v[120:123]
	v_mfma_f32_16x16x32_bf16 v[108:111], v[128:131], v[196:199], v[108:111]
	v_mfma_f32_16x16x32_bf16 v[104:107], v[136:139], v[196:199], v[104:107]
	v_mfma_f32_16x16x32_bf16 v[92:95], v[128:131], v[204:207], v[92:95]
	v_mfma_f32_16x16x32_bf16 v[88:91], v[136:139], v[204:207], v[88:91]
	v_mfma_f32_16x16x32_bf16 v[76:79], v[128:131], v[212:215], v[76:79]
	v_mfma_f32_16x16x32_bf16 v[72:75], v[136:139], v[212:215], v[72:75]
	v_mfma_f32_16x16x32_bf16 v[124:127], v[132:135], v[192:195], v[124:127]
	v_mfma_f32_16x16x32_bf16 v[120:123], v[140:143], v[192:195], v[120:123]
	v_mfma_f32_16x16x32_bf16 v[108:111], v[132:135], v[200:203], v[108:111]
	v_mfma_f32_16x16x32_bf16 v[104:107], v[140:143], v[200:203], v[104:107]
	v_mfma_f32_16x16x32_bf16 v[92:95], v[132:135], v[208:211], v[92:95]
	v_mfma_f32_16x16x32_bf16 v[88:91], v[140:143], v[208:211], v[88:91]
	v_mfma_f32_16x16x32_bf16 v[76:79], v[132:135], v[228:231], v[76:79]
	v_mfma_f32_16x16x32_bf16 v[72:75], v[140:143], v[228:231], v[72:75]
	v_mfma_f32_16x16x32_bf16 v[116:119], v[154:157], v[188:191], v[116:119]
	v_mfma_f32_16x16x32_bf16 v[112:115], v[166:169], v[188:191], v[112:115]
	v_mfma_f32_16x16x32_bf16 v[100:103], v[154:157], v[196:199], v[100:103]
	v_mfma_f32_16x16x32_bf16 v[96:99], v[166:169], v[196:199], v[96:99]
	v_mfma_f32_16x16x32_bf16 v[84:87], v[154:157], v[204:207], v[84:87]
	v_mfma_f32_16x16x32_bf16 v[80:83], v[166:169], v[204:207], v[80:83]
	v_mfma_f32_16x16x32_bf16 v[68:71], v[154:157], v[212:215], v[68:71]
	v_mfma_f32_16x16x32_bf16 v[64:67], v[166:169], v[212:215], v[64:67]
	v_mfma_f32_16x16x32_bf16 v[116:119], v[158:161], v[192:195], v[116:119]
	v_mfma_f32_16x16x32_bf16 v[112:115], v[184:187], v[192:195], v[112:115]
	v_mfma_f32_16x16x32_bf16 v[100:103], v[158:161], v[200:203], v[100:103]
	v_mfma_f32_16x16x32_bf16 v[96:99], v[184:187], v[200:203], v[96:99]
	v_mfma_f32_16x16x32_bf16 v[84:87], v[158:161], v[208:211], v[84:87]
	v_mfma_f32_16x16x32_bf16 v[80:83], v[184:187], v[208:211], v[80:83]
	v_mfma_f32_16x16x32_bf16 v[68:71], v[158:161], v[228:231], v[68:71]
	v_mfma_f32_16x16x32_bf16 v[64:67], v[184:187], v[228:231], v[64:67]
	s_setprio 0
	s_barrier
	s_add_i32 s28, s50, s36
	v_lshl_add_u64 v[170:171], v[170:171], 0, s[62:63]
	s_mov_b32 m0, s28
	ds_read_b128 v[188:191], v165 offset:49152
	ds_read_b128 v[192:195], v165 offset:50176
	ds_read_b128 v[196:199], v165 offset:51200
	ds_read_b128 v[200:203], v165 offset:52224
	ds_read_b128 v[204:207], v165 offset:53248
	ds_read_b128 v[208:211], v165 offset:54272
	ds_read_b128 v[212:215], v165 offset:55296
	ds_read_b128 v[228:231], v165 offset:56320
	global_load_lds_dwordx4 v[170:171], off
	s_add_i32 m0, s28, 0x2000
	s_add_u32 s26, s26, 0x40080
	v_lshl_add_u64 v[170:171], v[216:217], 0, s[62:63]
	s_addc_u32 s27, s27, 0
	s_add_i32 s28, s51, s36
	global_load_lds_dwordx4 v[170:171], off
	v_lshl_add_u64 v[170:171], s[26:27], 0, v[174:175]
	s_mov_b32 m0, s28
	s_nop 0
	global_load_lds_dwordx4 v[170:171], off
	v_lshl_add_u64 v[170:171], s[26:27], 0, v[144:145]
	s_add_i32 m0, s28, 0x2000
	s_nop 0
	global_load_lds_dwordx4 v[170:171], off
	v_lshl_add_u64 v[170:171], v[220:221], 0, s[62:63]
	s_mov_b32 m0, s41
	s_nop 0
	global_load_lds_dwordx4 v[170:171], off
	v_lshl_add_u64 v[170:171], v[232:233], 0, s[62:63]
	s_mov_b32 m0, s42
	s_nop 0
	global_load_lds_dwordx4 v[170:171], off
	s_waitcnt vmcnt(8)
	s_waitcnt lgkmcnt(0)
	s_barrier
	s_setprio 1
	s_waitcnt lgkmcnt(0)
	v_mfma_f32_16x16x32_bf16 v[60:63], v[128:131], v[188:191], v[60:63]
	v_mfma_f32_16x16x32_bf16 v[56:59], v[136:139], v[188:191], v[56:59]
	v_mfma_f32_16x16x32_bf16 v[44:47], v[128:131], v[196:199], v[44:47]
	v_mfma_f32_16x16x32_bf16 v[40:43], v[136:139], v[196:199], v[40:43]
	v_mfma_f32_16x16x32_bf16 v[28:31], v[128:131], v[204:207], v[28:31]
	v_mfma_f32_16x16x32_bf16 v[24:27], v[136:139], v[204:207], v[24:27]
	v_mfma_f32_16x16x32_bf16 v[12:15], v[128:131], v[212:215], v[12:15]
	v_mfma_f32_16x16x32_bf16 v[8:11], v[136:139], v[212:215], v[8:11]
	v_mfma_f32_16x16x32_bf16 v[60:63], v[132:135], v[192:195], v[60:63]
	v_mfma_f32_16x16x32_bf16 v[56:59], v[140:143], v[192:195], v[56:59]
	v_mfma_f32_16x16x32_bf16 v[44:47], v[132:135], v[200:203], v[44:47]
	v_mfma_f32_16x16x32_bf16 v[40:43], v[140:143], v[200:203], v[40:43]
	v_mfma_f32_16x16x32_bf16 v[28:31], v[132:135], v[208:211], v[28:31]
	v_mfma_f32_16x16x32_bf16 v[24:27], v[140:143], v[208:211], v[24:27]
	v_mfma_f32_16x16x32_bf16 v[12:15], v[132:135], v[228:231], v[12:15]
	v_mfma_f32_16x16x32_bf16 v[8:11], v[140:143], v[228:231], v[8:11]
	v_mfma_f32_16x16x32_bf16 v[52:55], v[154:157], v[188:191], v[52:55]
	v_mfma_f32_16x16x32_bf16 v[48:51], v[166:169], v[188:191], v[48:51]
	v_mfma_f32_16x16x32_bf16 v[36:39], v[154:157], v[196:199], v[36:39]
	v_mfma_f32_16x16x32_bf16 v[32:35], v[166:169], v[196:199], v[32:35]
	v_mfma_f32_16x16x32_bf16 v[20:23], v[154:157], v[204:207], v[20:23]
	v_mfma_f32_16x16x32_bf16 v[16:19], v[166:169], v[204:207], v[16:19]
	v_mfma_f32_16x16x32_bf16 v[4:7], v[154:157], v[212:215], v[4:7]
	v_mfma_f32_16x16x32_bf16 v[0:3], v[166:169], v[212:215], v[0:3]
	v_mfma_f32_16x16x32_bf16 v[52:55], v[158:161], v[192:195], v[52:55]
	v_mfma_f32_16x16x32_bf16 v[48:51], v[184:187], v[192:195], v[48:51]
	v_mfma_f32_16x16x32_bf16 v[36:39], v[158:161], v[200:203], v[36:39]
	v_mfma_f32_16x16x32_bf16 v[32:35], v[184:187], v[200:203], v[32:35]
	v_mfma_f32_16x16x32_bf16 v[20:23], v[158:161], v[208:211], v[20:23]
	v_mfma_f32_16x16x32_bf16 v[16:19], v[184:187], v[208:211], v[16:19]
	v_mfma_f32_16x16x32_bf16 v[4:7], v[158:161], v[228:231], v[4:7]
	v_mfma_f32_16x16x32_bf16 v[0:3], v[184:187], v[228:231], v[0:3]
	s_setprio 0
	s_barrier
	s_add_i32 s49, s49, 2
	s_add_u32 s24, s24, 0x100
	s_addc_u32 s25, s25, 0
	s_add_u32 s47, s47, 0x100
	s_addc_u32 s48, s48, 0
	s_cmp_gt_u32 s49, 13
	s_cbranch_scc0 .LBB0_964
	s_and_b64 vcc, exec, s[14:15]
	s_cbranch_vccz .LBB0_967
	s_barrier

.LBB0_1044:
	s_add_u32 s36, s6, 0xfffc0080
	s_addc_u32 s37, s7, -1
	s_add_i32 s57, 0, 0x10000
	s_cmp_eq_u32 s56, 12
	s_cselect_b32 s39, s29, s37
	s_cselect_b32 s38, s52, s36
	s_cselect_b32 s37, s27, s55
	s_cselect_b32 s36, s53, s54
	s_add_i32 s60, 0, 0x14000
	v_add_u32_e32 v140, s57, v185
	v_add_u32_e32 v162, s60, v185
	ds_read_b128 v[128:131], v140
	ds_read_b128 v[132:135], v140 offset:1024
	ds_read_b128 v[136:139], v140 offset:2048
	ds_read_b128 v[140:143], v140 offset:3072
	ds_read_b128 v[144:147], v162
	ds_read_b128 v[148:151], v162 offset:1024
	ds_read_b128 v[152:155], v162 offset:2048
	ds_read_b128 v[162:165], v162 offset:3072
	v_lshl_add_u64 v[170:171], s[6:7], 0, v[158:159]
	s_add_i32 m0, s45, 0xc000
	ds_read_b128 v[166:169], v190
	ds_read_b128 v[192:195], v190 offset:1024
	ds_read_b128 v[196:199], v190 offset:2048
	ds_read_b128 v[200:203], v190 offset:3072
	ds_read_b128 v[204:207], v190 offset:4096
	ds_read_b128 v[208:211], v190 offset:5120
	ds_read_b128 v[212:215], v190 offset:6144
	ds_read_b128 v[228:231], v190 offset:7168
	global_load_lds_dwordx4 v[170:171], off
	v_lshl_add_u64 v[170:171], s[6:7], 0, v[160:161]
	s_add_i32 m0, s45, 0xe000
	s_nop 0
	global_load_lds_dwordx4 v[170:171], off
	s_waitcnt vmcnt(8)
	s_waitcnt lgkmcnt(0)
	s_barrier
	s_setprio 1
	s_waitcnt lgkmcnt(0)
	v_mfma_f32_16x16x32_bf16 v[124:127], v[128:131], v[166:169], v[124:127]
	v_mfma_f32_16x16x32_bf16 v[120:123], v[136:139], v[166:169], v[120:123]
	v_mfma_f32_16x16x32_bf16 v[108:111], v[128:131], v[196:199], v[108:111]
	v_mfma_f32_16x16x32_bf16 v[104:107], v[136:139], v[196:199], v[104:107]
	v_mfma_f32_16x16x32_bf16 v[92:95], v[128:131], v[204:207], v[92:95]
	v_mfma_f32_16x16x32_bf16 v[88:91], v[136:139], v[204:207], v[88:91]
	v_mfma_f32_16x16x32_bf16 v[76:79], v[128:131], v[212:215], v[76:79]
	v_mfma_f32_16x16x32_bf16 v[72:75], v[136:139], v[212:215], v[72:75]
	v_mfma_f32_16x16x32_bf16 v[124:127], v[132:135], v[192:195], v[124:127]
	v_mfma_f32_16x16x32_bf16 v[120:123], v[140:143], v[192:195], v[120:123]
	v_mfma_f32_16x16x32_bf16 v[108:111], v[132:135], v[200:203], v[108:111]
	v_mfma_f32_16x16x32_bf16 v[104:107], v[140:143], v[200:203], v[104:107]
	v_mfma_f32_16x16x32_bf16 v[92:95], v[132:135], v[208:211], v[92:95]
	v_mfma_f32_16x16x32_bf16 v[88:91], v[140:143], v[208:211], v[88:91]
	v_mfma_f32_16x16x32_bf16 v[76:79], v[132:135], v[228:231], v[76:79]
	v_mfma_f32_16x16x32_bf16 v[72:75], v[140:143], v[228:231], v[72:75]
	v_mfma_f32_16x16x32_bf16 v[116:119], v[144:147], v[166:169], v[116:119]
	v_mfma_f32_16x16x32_bf16 v[112:115], v[152:155], v[166:169], v[112:115]
	v_mfma_f32_16x16x32_bf16 v[100:103], v[144:147], v[196:199], v[100:103]
	v_mfma_f32_16x16x32_bf16 v[96:99], v[152:155], v[196:199], v[96:99]
	v_mfma_f32_16x16x32_bf16 v[84:87], v[144:147], v[204:207], v[84:87]
	v_mfma_f32_16x16x32_bf16 v[80:83], v[152:155], v[204:207], v[80:83]
	v_mfma_f32_16x16x32_bf16 v[68:71], v[144:147], v[212:215], v[68:71]
	v_mfma_f32_16x16x32_bf16 v[64:67], v[152:155], v[212:215], v[64:67]
	v_mfma_f32_16x16x32_bf16 v[116:119], v[148:151], v[192:195], v[116:119]
	v_mfma_f32_16x16x32_bf16 v[112:115], v[162:165], v[192:195], v[112:115]
	v_mfma_f32_16x16x32_bf16 v[100:103], v[148:151], v[200:203], v[100:103]
	v_mfma_f32_16x16x32_bf16 v[96:99], v[162:165], v[200:203], v[96:99]
	v_mfma_f32_16x16x32_bf16 v[84:87], v[148:151], v[208:211], v[84:87]
	v_mfma_f32_16x16x32_bf16 v[80:83], v[162:165], v[208:211], v[80:83]
	v_mfma_f32_16x16x32_bf16 v[68:71], v[148:151], v[228:231], v[68:71]
	v_mfma_f32_16x16x32_bf16 v[64:67], v[162:165], v[228:231], v[64:67]
	s_setprio 0
	s_barrier
	s_add_i32 s57, s57, s44
	v_lshl_add_u64 v[170:171], s[36:37], 0, v[174:175]
	s_mov_b32 m0, s57
	ds_read_b128 v[166:169], v190 offset:16384
	ds_read_b128 v[192:195], v190 offset:17408
	ds_read_b128 v[196:199], v190 offset:18432
	ds_read_b128 v[200:203], v190 offset:19456
	ds_read_b128 v[204:207], v190 offset:20480
	ds_read_b128 v[208:211], v190 offset:21504
	ds_read_b128 v[212:215], v190 offset:22528
	ds_read_b128 v[228:231], v190 offset:23552
	global_load_lds_dwordx4 v[170:171], off
	s_add_i32 m0, s57, 0x2000
	s_add_u32 s58, s36, 0x40000
	v_lshl_add_u64 v[216:217], s[36:37], 0, v[156:157]
	s_addc_u32 s59, s37, 0
	s_add_i32 s57, s60, s44
	global_load_lds_dwordx4 v[216:217], off
	v_lshl_add_u64 v[220:221], s[58:59], 0, v[174:175]
	s_mov_b32 m0, s57
	v_lshl_add_u64 v[232:233], s[38:39], 0, v[156:157]
	global_load_lds_dwordx4 v[220:221], off
	v_lshl_add_u64 v[220:221], s[58:59], 0, v[156:157]
	s_add_i32 m0, s57, 0x2000
	s_nop 0
	global_load_lds_dwordx4 v[220:221], off
	v_lshl_add_u64 v[220:221], s[38:39], 0, v[174:175]
	s_mov_b32 m0, s45
	s_nop 0
	global_load_lds_dwordx4 v[220:221], off
	s_mov_b32 m0, s46
	s_nop 0
	global_load_lds_dwordx4 v[232:233], off
	s_waitcnt vmcnt(8)
	s_waitcnt lgkmcnt(0)
	s_barrier
	s_setprio 1
	s_waitcnt lgkmcnt(0)
	v_mfma_f32_16x16x32_bf16 v[60:63], v[128:131], v[166:169], v[60:63]
	v_mfma_f32_16x16x32_bf16 v[56:59], v[136:139], v[166:169], v[56:59]
	v_mfma_f32_16x16x32_bf16 v[44:47], v[128:131], v[196:199], v[44:47]
	v_mfma_f32_16x16x32_bf16 v[40:43], v[136:139], v[196:199], v[40:43]
	v_mfma_f32_16x16x32_bf16 v[28:31], v[128:131], v[204:207], v[28:31]
	v_mfma_f32_16x16x32_bf16 v[24:27], v[136:139], v[204:207], v[24:27]
	v_mfma_f32_16x16x32_bf16 v[12:15], v[128:131], v[212:215], v[12:15]
	v_mfma_f32_16x16x32_bf16 v[8:11], v[136:139], v[212:215], v[8:11]
	v_mfma_f32_16x16x32_bf16 v[60:63], v[132:135], v[192:195], v[60:63]
	v_mfma_f32_16x16x32_bf16 v[56:59], v[140:143], v[192:195], v[56:59]
	v_mfma_f32_16x16x32_bf16 v[44:47], v[132:135], v[200:203], v[44:47]
	v_mfma_f32_16x16x32_bf16 v[40:43], v[140:143], v[200:203], v[40:43]
	v_mfma_f32_16x16x32_bf16 v[28:31], v[132:135], v[208:211], v[28:31]
	v_mfma_f32_16x16x32_bf16 v[24:27], v[140:143], v[208:211], v[24:27]
	v_mfma_f32_16x16x32_bf16 v[12:15], v[132:135], v[228:231], v[12:15]
	v_mfma_f32_16x16x32_bf16 v[8:11], v[140:143], v[228:231], v[8:11]
	v_mfma_f32_16x16x32_bf16 v[52:55], v[144:147], v[166:169], v[52:55]
	v_mfma_f32_16x16x32_bf16 v[48:51], v[152:155], v[166:169], v[48:51]
	v_mfma_f32_16x16x32_bf16 v[36:39], v[144:147], v[196:199], v[36:39]
	v_mfma_f32_16x16x32_bf16 v[32:35], v[152:155], v[196:199], v[32:35]
	v_mfma_f32_16x16x32_bf16 v[20:23], v[144:147], v[204:207], v[20:23]
	v_mfma_f32_16x16x32_bf16 v[16:19], v[152:155], v[204:207], v[16:19]
	v_mfma_f32_16x16x32_bf16 v[4:7], v[144:147], v[212:215], v[4:7]
	v_mfma_f32_16x16x32_bf16 v[0:3], v[152:155], v[212:215], v[0:3]
	v_mfma_f32_16x16x32_bf16 v[52:55], v[148:151], v[192:195], v[52:55]
	v_mfma_f32_16x16x32_bf16 v[48:51], v[162:165], v[192:195], v[48:51]
	v_mfma_f32_16x16x32_bf16 v[36:39], v[148:151], v[200:203], v[36:39]
	v_mfma_f32_16x16x32_bf16 v[32:35], v[162:165], v[200:203], v[32:35]
	v_mfma_f32_16x16x32_bf16 v[20:23], v[148:151], v[208:211], v[20:23]
	v_mfma_f32_16x16x32_bf16 v[16:19], v[162:165], v[208:211], v[16:19]
	v_mfma_f32_16x16x32_bf16 v[4:7], v[148:151], v[228:231], v[4:7]
	v_mfma_f32_16x16x32_bf16 v[0:3], v[162:165], v[228:231], v[0:3]
	s_setprio 0
	s_barrier
	s_add_i32 s57, 0, 0x18000
	s_add_i32 s58, 0, 0x1c000
	v_add_u32_e32 v140, s57, v185
	v_add_u32_e32 v162, s58, v185
	ds_read_b128 v[128:131], v140
	ds_read_b128 v[132:135], v140 offset:1024
	ds_read_b128 v[136:139], v140 offset:2048
	ds_read_b128 v[140:143], v140 offset:3072
	ds_read_b128 v[144:147], v162
	ds_read_b128 v[148:151], v162 offset:1024
	ds_read_b128 v[152:155], v162 offset:2048
	ds_read_b128 v[162:165], v162 offset:3072
	s_add_u32 s38, s38, 0x40000
	s_addc_u32 s39, s39, 0
	s_mov_b32 m0, s33
	v_lshl_add_u64 v[234:235], s[38:39], 0, v[174:175]
	ds_read_b128 v[166:169], v190 offset:32768
	ds_read_b128 v[192:195], v190 offset:33792
	ds_read_b128 v[196:199], v190 offset:34816
	ds_read_b128 v[200:203], v190 offset:35840
	ds_read_b128 v[204:207], v190 offset:36864
	ds_read_b128 v[208:211], v190 offset:37888
	ds_read_b128 v[212:215], v190 offset:38912
	ds_read_b128 v[228:231], v190 offset:39936
	global_load_lds_dwordx4 v[234:235], off
	v_lshl_add_u64 v[234:235], s[38:39], 0, v[156:157]
	s_mov_b32 m0, s47
	s_nop 0
	global_load_lds_dwordx4 v[234:235], off
	s_waitcnt vmcnt(8)
	s_waitcnt lgkmcnt(0)
	s_barrier
	s_setprio 1
	s_waitcnt lgkmcnt(0)
	v_mfma_f32_16x16x32_bf16 v[124:127], v[128:131], v[166:169], v[124:127]
	v_mfma_f32_16x16x32_bf16 v[120:123], v[136:139], v[166:169], v[120:123]
	v_mfma_f32_16x16x32_bf16 v[108:111], v[128:131], v[196:199], v[108:111]
	v_mfma_f32_16x16x32_bf16 v[104:107], v[136:139], v[196:199], v[104:107]
	v_mfma_f32_16x16x32_bf16 v[92:95], v[128:131], v[204:207], v[92:95]
	v_mfma_f32_16x16x32_bf16 v[88:91], v[136:139], v[204:207], v[88:91]
	v_mfma_f32_16x16x32_bf16 v[76:79], v[128:131], v[212:215], v[76:79]
	v_mfma_f32_16x16x32_bf16 v[72:75], v[136:139], v[212:215], v[72:75]
	v_mfma_f32_16x16x32_bf16 v[124:127], v[132:135], v[192:195], v[124:127]
	v_mfma_f32_16x16x32_bf16 v[120:123], v[140:143], v[192:195], v[120:123]
	v_mfma_f32_16x16x32_bf16 v[108:111], v[132:135], v[200:203], v[108:111]
	v_mfma_f32_16x16x32_bf16 v[104:107], v[140:143], v[200:203], v[104:107]
	v_mfma_f32_16x16x32_bf16 v[92:95], v[132:135], v[208:211], v[92:95]
	v_mfma_f32_16x16x32_bf16 v[88:91], v[140:143], v[208:211], v[88:91]
	v_mfma_f32_16x16x32_bf16 v[76:79], v[132:135], v[228:231], v[76:79]
	v_mfma_f32_16x16x32_bf16 v[72:75], v[140:143], v[228:231], v[72:75]
	v_mfma_f32_16x16x32_bf16 v[116:119], v[144:147], v[166:169], v[116:119]
	v_mfma_f32_16x16x32_bf16 v[112:115], v[152:155], v[166:169], v[112:115]
	v_mfma_f32_16x16x32_bf16 v[100:103], v[144:147], v[196:199], v[100:103]
	v_mfma_f32_16x16x32_bf16 v[96:99], v[152:155], v[196:199], v[96:99]
	v_mfma_f32_16x16x32_bf16 v[84:87], v[144:147], v[204:207], v[84:87]
	v_mfma_f32_16x16x32_bf16 v[80:83], v[152:155], v[204:207], v[80:83]
	v_mfma_f32_16x16x32_bf16 v[68:71], v[144:147], v[212:215], v[68:71]
	v_mfma_f32_16x16x32_bf16 v[64:67], v[152:155], v[212:215], v[64:67]
	v_mfma_f32_16x16x32_bf16 v[116:119], v[148:151], v[192:195], v[116:119]
	v_mfma_f32_16x16x32_bf16 v[112:115], v[162:165], v[192:195], v[112:115]
	v_mfma_f32_16x16x32_bf16 v[100:103], v[148:151], v[200:203], v[100:103]
	v_mfma_f32_16x16x32_bf16 v[96:99], v[162:165], v[200:203], v[96:99]
	v_mfma_f32_16x16x32_bf16 v[84:87], v[148:151], v[208:211], v[84:87]
	v_mfma_f32_16x16x32_bf16 v[80:83], v[162:165], v[208:211], v[80:83]
	v_mfma_f32_16x16x32_bf16 v[68:71], v[148:151], v[228:231], v[68:71]
	v_mfma_f32_16x16x32_bf16 v[64:67], v[162:165], v[228:231], v[64:67]
	s_setprio 0
	s_barrier
	s_add_i32 s38, s57, s44
	v_lshl_add_u64 v[170:171], v[170:171], 0, s[62:63]
	s_mov_b32 m0, s38
	ds_read_b128 v[166:169], v190 offset:49152
	ds_read_b128 v[192:195], v190 offset:50176
	ds_read_b128 v[196:199], v190 offset:51200
	ds_read_b128 v[200:203], v190 offset:52224
	ds_read_b128 v[204:207], v190 offset:53248
	ds_read_b128 v[208:211], v190 offset:54272
	ds_read_b128 v[212:215], v190 offset:55296
	ds_read_b128 v[228:231], v190 offset:56320
	global_load_lds_dwordx4 v[170:171], off
	s_add_i32 m0, s38, 0x2000
	s_add_u32 s36, s36, 0x40080
	v_lshl_add_u64 v[170:171], v[216:217], 0, s[62:63]
	s_addc_u32 s37, s37, 0
	s_add_i32 s38, s58, s44
	global_load_lds_dwordx4 v[170:171], off
	v_lshl_add_u64 v[170:171], s[36:37], 0, v[174:175]
	s_mov_b32 m0, s38
	s_nop 0
	global_load_lds_dwordx4 v[170:171], off
	v_lshl_add_u64 v[170:171], s[36:37], 0, v[156:157]
	s_add_i32 m0, s38, 0x2000
	s_nop 0
	global_load_lds_dwordx4 v[170:171], off
	v_lshl_add_u64 v[170:171], v[220:221], 0, s[62:63]
	s_mov_b32 m0, s49
	s_nop 0
	global_load_lds_dwordx4 v[170:171], off
	v_lshl_add_u64 v[170:171], v[232:233], 0, s[62:63]
	s_mov_b32 m0, s50
	s_nop 0
	global_load_lds_dwordx4 v[170:171], off
	s_waitcnt vmcnt(8)
	s_waitcnt lgkmcnt(0)
	s_barrier
	s_setprio 1
	s_waitcnt lgkmcnt(0)
	v_mfma_f32_16x16x32_bf16 v[60:63], v[128:131], v[166:169], v[60:63]
	v_mfma_f32_16x16x32_bf16 v[56:59], v[136:139], v[166:169], v[56:59]
	v_mfma_f32_16x16x32_bf16 v[44:47], v[128:131], v[196:199], v[44:47]
	v_mfma_f32_16x16x32_bf16 v[40:43], v[136:139], v[196:199], v[40:43]
	v_mfma_f32_16x16x32_bf16 v[28:31], v[128:131], v[204:207], v[28:31]
	v_mfma_f32_16x16x32_bf16 v[24:27], v[136:139], v[204:207], v[24:27]
	v_mfma_f32_16x16x32_bf16 v[12:15], v[128:131], v[212:215], v[12:15]
	v_mfma_f32_16x16x32_bf16 v[8:11], v[136:139], v[212:215], v[8:11]
	v_mfma_f32_16x16x32_bf16 v[60:63], v[132:135], v[192:195], v[60:63]
	v_mfma_f32_16x16x32_bf16 v[56:59], v[140:143], v[192:195], v[56:59]
	v_mfma_f32_16x16x32_bf16 v[44:47], v[132:135], v[200:203], v[44:47]
	v_mfma_f32_16x16x32_bf16 v[40:43], v[140:143], v[200:203], v[40:43]
	v_mfma_f32_16x16x32_bf16 v[28:31], v[132:135], v[208:211], v[28:31]
	v_mfma_f32_16x16x32_bf16 v[24:27], v[140:143], v[208:211], v[24:27]
	v_mfma_f32_16x16x32_bf16 v[12:15], v[132:135], v[228:231], v[12:15]
	v_mfma_f32_16x16x32_bf16 v[8:11], v[140:143], v[228:231], v[8:11]
	v_mfma_f32_16x16x32_bf16 v[52:55], v[144:147], v[166:169], v[52:55]
	v_mfma_f32_16x16x32_bf16 v[48:51], v[152:155], v[166:169], v[48:51]
	v_mfma_f32_16x16x32_bf16 v[36:39], v[144:147], v[196:199], v[36:39]
	v_mfma_f32_16x16x32_bf16 v[32:35], v[152:155], v[196:199], v[32:35]
	v_mfma_f32_16x16x32_bf16 v[20:23], v[144:147], v[204:207], v[20:23]
	v_mfma_f32_16x16x32_bf16 v[16:19], v[152:155], v[204:207], v[16:19]
	v_mfma_f32_16x16x32_bf16 v[4:7], v[144:147], v[212:215], v[4:7]
	v_mfma_f32_16x16x32_bf16 v[0:3], v[152:155], v[212:215], v[0:3]
	v_mfma_f32_16x16x32_bf16 v[52:55], v[148:151], v[192:195], v[52:55]
	v_mfma_f32_16x16x32_bf16 v[48:51], v[162:165], v[192:195], v[48:51]
	v_mfma_f32_16x16x32_bf16 v[36:39], v[148:151], v[200:203], v[36:39]
	v_mfma_f32_16x16x32_bf16 v[32:35], v[162:165], v[200:203], v[32:35]
	v_mfma_f32_16x16x32_bf16 v[20:23], v[148:151], v[208:211], v[20:23]
	v_mfma_f32_16x16x32_bf16 v[16:19], v[162:165], v[208:211], v[16:19]
	v_mfma_f32_16x16x32_bf16 v[4:7], v[148:151], v[228:231], v[4:7]
	v_mfma_f32_16x16x32_bf16 v[0:3], v[162:165], v[228:231], v[0:3]
	s_setprio 0
	s_barrier
	s_add_i32 s56, s56, 2
	s_add_u32 s6, s6, 0x100
	s_addc_u32 s7, s7, 0
	s_add_u32 s54, s54, 0x100
	s_addc_u32 s55, s55, 0
	s_cmp_gt_u32 s56, 13
	s_cbranch_scc0 .LBB0_1044
	s_and_b64 vcc, exec, s[20:21]
	s_cbranch_vccz .LBB0_1047
	s_barrier
